# P1 tile decode: tn -> (tn+4)%24 for t>=768 (rounds 3-5) so the expensive VgT-epilogue tiles are not done twice by the same 25% of CUs; bijective remap, arithmetic unchanged
# speedup vs baseline: 1.0000x; 1.0000x over previous
.LBB0_148:
	s_mul_hi_i32 s0, s86, 0x2aaaaaab
	s_lshr_b32 s1, s0, 31
	s_ashr_i32 s0, s0, 2
	s_add_i32 s96, s0, s1
	s_mul_i32 s0, s96, 24
	s_ashr_i32 s97, s96, 31
	s_sub_i32 s94, s86, s0
	s_cmpk_ge_i32 s86, 0x300
	s_cselect_b32 s1, 4, 0
	s_add_i32 s94, s94, s1
	s_cmpk_ge_i32 s94, 24
	s_cselect_b32 s1, 24, 0
	s_sub_i32 s94, s94, s1
	s_lshl_b64 s[34:35], s[96:97], 19
	v_readlane_b32 s52, v249, 16
	s_add_u32 s92, s48, s34
	v_readlane_b32 s64, v249, 28
	v_readlane_b32 s65, v249, 29
	s_addc_u32 s93, s49, s35
	s_ashr_i32 s95, s94, 31
	v_readlane_b32 s66, v249, 30
	v_readlane_b32 s67, v249, 31
	s_mov_b64 s[28:29], s[64:65]
	s_lshl_b64 s[12:13], s[94:95], 19
	s_mov_b64 s[30:31], s[66:67]
	s_add_u32 s28, s30, s12
	s_addc_u32 s29, s31, s13
	s_and_b32 s0, s94, -4
	s_cmp_lg_u32 s0, 12
	s_mov_b64 s[8:9], -1
	v_readlane_b32 s53, v249, 17
	v_readlane_b32 s54, v249, 18
	v_readlane_b32 s55, v249, 19
	v_readlane_b32 s56, v249, 20
	v_readlane_b32 s57, v249, 21
	v_readlane_b32 s58, v249, 22
	v_readlane_b32 s59, v249, 23
	v_readlane_b32 s60, v249, 24
	v_readlane_b32 s61, v249, 25
	v_readlane_b32 s62, v249, 26
	v_readlane_b32 s63, v249, 27
	s_cbranch_scc0 .LBB0_184
	v_mov_b32_e32 v2, v0
	v_readfirstlane_b32 s0, v0
	v_lshlrev_b32_e32 v3, 4, v2
	v_bfe_i32 v2, v2, 27, 1
	v_lshrrev_b32_e32 v2, 22, v2
	v_add_u32_e32 v2, v3, v2
	v_ashrrev_i32_e32 v10, 10, v2
	v_mul_i32_i24_e32 v2, 0x400, v10
	v_sub_u32_e32 v2, v3, v2
	v_add_u32_e32 v4, 0x2000, v3
	v_lshrrev_b32_e32 v3, 4, v2
	v_bitop3_b32 v2, v3, v2, 32 bitop3:0x6c
	v_ashrrev_i32_e32 v5, 31, v2
	v_lshrrev_b32_e32 v5, 26, v5
	v_add_u32_e32 v5, v2, v5
	v_ashrrev_i32_e32 v12, 6, v5
	v_and_b32_e32 v5, 0xc0, v5
	v_sub_u32_e32 v2, v2, v5
	v_ashrrev_i16_sdwa v14, v217, sext(v2) dst_sel:DWORD dst_unused:UNUSED_PAD src0_sel:DWORD src1_sel:BYTE_0
	v_ashrrev_i32_e32 v2, 31, v4
	v_lshrrev_b32_e32 v2, 22, v2
	v_add_u32_e32 v2, v4, v2
	v_ashrrev_i32_e32 v11, 10, v2
	v_mul_i32_i24_e32 v2, 0x400, v11
	v_sub_u32_e32 v2, v4, v2
	v_lshrrev_b32_e32 v4, 4, v2
	v_bitop3_b32 v2, v4, v2, 32 bitop3:0x6c
	v_ashrrev_i32_e32 v5, 31, v2
	v_lshrrev_b32_e32 v5, 26, v5
	v_lshlrev_b32_e32 v3, 3, v10
	v_add_u32_e32 v5, v2, v5
	v_and_b32_e32 v3, 0x3ffff0, v3
	v_lshlrev_b32_e32 v6, 5, v10
	v_lshlrev_b32_e32 v4, 3, v11
	v_ashrrev_i32_e32 v15, 6, v5
	v_and_b32_e32 v5, 0xc0, v5
	v_add_u32_e32 v3, v12, v3
	v_and_b32_e32 v13, 32, v6
	v_and_b32_e32 v4, 0x3ffff0, v4
	v_lshlrev_b32_e32 v6, 5, v11
	v_sub_u32_e32 v2, v2, v5
	s_lshl_b32 s0, s0, 4
	v_add_u32_e32 v4, v15, v4
	v_and_b32_e32 v16, 32, v6
	v_ashrrev_i16_sdwa v17, v217, sext(v2) dst_sel:DWORD dst_unused:UNUSED_PAD src0_sel:DWORD src1_sel:BYTE_0
	v_lshl_or_b32 v2, v3, 10, v13
	v_lshl_or_b32 v3, v4, 10, v16
	s_and_b32 s14, s0, 0xfffffc00
	v_add_u32_sdwa v164, v2, sext(v14) dst_sel:DWORD dst_unused:UNUSED_PAD src0_sel:DWORD src1_sel:WORD_0
	v_add_u32_sdwa v130, v3, sext(v17) dst_sel:DWORD dst_unused:UNUSED_PAD src0_sel:DWORD src1_sel:WORD_0
	v_lshlrev_b64 v[18:19], 1, v[164:165]
	s_add_i32 s87, s14, 0x10000
	v_mov_b32_e32 v131, v165
	v_lshl_add_u64 v[2:3], s[92:93], 0, v[18:19]
	s_mov_b32 m0, s87
	v_lshlrev_b64 v[20:21], 1, v[130:131]
	s_add_i32 s88, s14, 0x12000
	global_load_lds_dwordx4 v[2:3], off
	v_lshl_add_u64 v[6:7], s[92:93], 0, v[20:21]
	s_mov_b32 m0, s88
	s_add_i32 s89, s14, 0x2000
	global_load_lds_dwordx4 v[6:7], off
	v_lshl_add_u64 v[8:9], s[28:29], 0, v[18:19]
	s_mov_b32 m0, s14
	s_add_u32 s8, s92, 0x40000
	global_load_lds_dwordx4 v[8:9], off
	v_lshl_add_u64 v[4:5], s[28:29], 0, v[20:21]
	s_mov_b32 m0, s89
	s_addc_u32 s9, s93, 0
	s_add_i32 s90, s14, 0x14000
	global_load_lds_dwordx4 v[4:5], off
	v_lshl_add_u64 v[22:23], s[8:9], 0, v[18:19]
	s_mov_b32 m0, s90
	s_add_i32 s91, s14, 0x16000
	global_load_lds_dwordx4 v[22:23], off
	v_lshl_add_u64 v[22:23], s[8:9], 0, v[20:21]
	s_add_u32 s8, s28, 0x40000
	s_mov_b32 m0, s91
	s_addc_u32 s9, s29, 0
	s_add_i32 s95, s14, 0x4000
	global_load_lds_dwordx4 v[22:23], off
	v_lshl_add_u64 v[18:19], s[8:9], 0, v[18:19]
	s_mov_b32 m0, s95
	s_add_i32 s97, s14, 0x6000
	global_load_lds_dwordx4 v[18:19], off
	v_lshl_add_u64 v[18:19], s[8:9], 0, v[20:21]
	s_mov_b32 m0, s97
	v_readlane_b32 s0, v248, 0
	global_load_lds_dwordx4 v[18:19], off
	v_readlane_b32 s1, v248, 1
	s_and_saveexec_b64 s[8:9], s[0:1]
	s_cbranch_execz .LBB0_151
	s_barrier
